# v3b + relaxed first-iteration waits also in w_in and down/w_out loops
# baseline (speedup 1.0000x reference)
.LBB0_566:
	s_add_u32 s30, s0, 0xfffc0080
	s_addc_u32 s31, s1, -1
	s_add_i32 s52, 0, 0x10000
	s_cmp_eq_u32 s51, 12
	s_cselect_b32 s35, s3, s31
	s_cselect_b32 s34, s25, s30
	s_cselect_b32 s31, s23, s50
	s_cselect_b32 s30, s48, s49
	s_add_i32 s54, 0, 0x14000
	v_add_u32_e32 v158, s52, v199
	v_add_u32_e32 v174, s54, v199
	ds_read_b128 v[134:137], v158
	ds_read_b128 v[150:153], v158 offset:1024
	ds_read_b128 v[154:157], v158 offset:2048
	ds_read_b128 v[158:161], v158 offset:3072
	ds_read_b128 v[162:165], v174
	ds_read_b128 v[166:169], v174 offset:1024
	ds_read_b128 v[170:173], v174 offset:2048
	ds_read_b128 v[182:185], v174 offset:3072
	v_lshl_add_u64 v[174:175], s[0:1], 0, v[146:147]
	s_add_i32 m0, s39, 0xc000
	ds_read_b128 v[186:189], v201
	ds_read_b128 v[202:205], v201 offset:1024
	ds_read_b128 v[206:209], v201 offset:2048
	ds_read_b128 v[210:213], v201 offset:3072
	ds_read_b128 v[214:217], v201 offset:4096
	ds_read_b128 v[218:221], v201 offset:5120
	ds_read_b128 v[222:225], v201 offset:6144
	ds_read_b128 v[226:229], v201 offset:7168
	global_load_lds_dwordx4 v[174:175], off
	v_lshl_add_u64 v[174:175], s[0:1], 0, v[148:149]
	s_add_i32 m0, s39, 0xe000
	s_nop 0
	global_load_lds_dwordx4 v[174:175], off
	s_cmp_eq_i32 s51, -2
	s_cselect_b32 s98, s2, 0
	s_cmp_lg_u32 s98, 0
	s_cbranch_scc1 .Lga_relax_l1w1
	s_waitcnt vmcnt(8)
	s_branch .Lga_join_l1w1
.Lga_relax_l1w1:
	s_waitcnt vmcnt(24)
.Lga_join_l1w1:
	s_waitcnt lgkmcnt(0)
	s_barrier
	s_setprio 1
	s_waitcnt lgkmcnt(0)
	v_mfma_f32_16x16x32_bf16 v[130:133], v[134:137], v[186:189], v[130:133]
	v_mfma_f32_16x16x32_bf16 v[130:133], v[150:153], v[202:205], v[130:133]
	v_mfma_f32_16x16x32_bf16 v[126:129], v[154:157], v[186:189], v[126:129]
	v_mfma_f32_16x16x32_bf16 v[126:129], v[158:161], v[202:205], v[126:129]
	v_mfma_f32_16x16x32_bf16 v[114:117], v[134:137], v[206:209], v[114:117]
	v_mfma_f32_16x16x32_bf16 v[114:117], v[150:153], v[210:213], v[114:117]
	v_mfma_f32_16x16x32_bf16 v[110:113], v[154:157], v[206:209], v[110:113]
	v_mfma_f32_16x16x32_bf16 v[110:113], v[158:161], v[210:213], v[110:113]
	v_mfma_f32_16x16x32_bf16 v[98:101], v[134:137], v[214:217], v[98:101]
	v_mfma_f32_16x16x32_bf16 v[98:101], v[150:153], v[218:221], v[98:101]
	v_mfma_f32_16x16x32_bf16 v[94:97], v[154:157], v[214:217], v[94:97]
	v_mfma_f32_16x16x32_bf16 v[94:97], v[158:161], v[218:221], v[94:97]
	v_mfma_f32_16x16x32_bf16 v[82:85], v[134:137], v[222:225], v[82:85]
	v_mfma_f32_16x16x32_bf16 v[82:85], v[150:153], v[226:229], v[82:85]
	v_mfma_f32_16x16x32_bf16 v[78:81], v[154:157], v[222:225], v[78:81]
	v_mfma_f32_16x16x32_bf16 v[78:81], v[158:161], v[226:229], v[78:81]
	s_setprio 0
	s_setprio 1
	v_mfma_f32_16x16x32_bf16 v[122:125], v[162:165], v[186:189], v[122:125]
	v_mfma_f32_16x16x32_bf16 v[122:125], v[166:169], v[202:205], v[122:125]
	v_mfma_f32_16x16x32_bf16 v[118:121], v[170:173], v[186:189], v[118:121]
	v_mfma_f32_16x16x32_bf16 v[118:121], v[182:185], v[202:205], v[118:121]
	v_mfma_f32_16x16x32_bf16 v[106:109], v[162:165], v[206:209], v[106:109]
	v_mfma_f32_16x16x32_bf16 v[106:109], v[166:169], v[210:213], v[106:109]
	v_mfma_f32_16x16x32_bf16 v[102:105], v[170:173], v[206:209], v[102:105]
	v_mfma_f32_16x16x32_bf16 v[102:105], v[182:185], v[210:213], v[102:105]
	v_mfma_f32_16x16x32_bf16 v[90:93], v[162:165], v[214:217], v[90:93]
	v_mfma_f32_16x16x32_bf16 v[90:93], v[166:169], v[218:221], v[90:93]
	v_mfma_f32_16x16x32_bf16 v[86:89], v[170:173], v[214:217], v[86:89]
	v_mfma_f32_16x16x32_bf16 v[86:89], v[182:185], v[218:221], v[86:89]
	v_mfma_f32_16x16x32_bf16 v[74:77], v[162:165], v[222:225], v[74:77]
	v_mfma_f32_16x16x32_bf16 v[74:77], v[166:169], v[226:229], v[74:77]
	v_mfma_f32_16x16x32_bf16 v[70:73], v[170:173], v[222:225], v[70:73]
	v_mfma_f32_16x16x32_bf16 v[70:73], v[182:185], v[226:229], v[70:73]
	s_setprio 0
	s_barrier
	s_add_i32 s52, s52, s36
	v_lshl_add_u64 v[174:175], s[30:31], 0, v[0:1]
	s_mov_b32 m0, s52
	ds_read_b128 v[186:189], v201 offset:16384
	ds_read_b128 v[202:205], v201 offset:17408
	ds_read_b128 v[206:209], v201 offset:18432
	ds_read_b128 v[210:213], v201 offset:19456
	ds_read_b128 v[214:217], v201 offset:20480
	ds_read_b128 v[218:221], v201 offset:21504
	ds_read_b128 v[222:225], v201 offset:22528
	ds_read_b128 v[226:229], v201 offset:23552
	global_load_lds_dwordx4 v[174:175], off
	s_add_i32 m0, s52, 0x2000
	s_add_u32 s52, s30, 0x40000
	v_lshl_add_u64 v[190:191], s[30:31], 0, v[14:15]
	s_addc_u32 s53, s31, 0
	s_add_i32 s54, s54, s36
	global_load_lds_dwordx4 v[190:191], off
	v_lshl_add_u64 v[230:231], s[52:53], 0, v[0:1]
	s_mov_b32 m0, s54
	v_lshl_add_u64 v[232:233], s[34:35], 0, v[138:139]
	global_load_lds_dwordx4 v[230:231], off
	v_lshl_add_u64 v[230:231], s[52:53], 0, v[14:15]
	s_add_i32 m0, s54, 0x2000
	s_nop 0
	global_load_lds_dwordx4 v[230:231], off
	v_lshl_add_u64 v[230:231], s[34:35], 0, v[140:141]
	s_mov_b32 m0, s39
	s_nop 0
	global_load_lds_dwordx4 v[230:231], off
	s_mov_b32 m0, s40
	s_nop 0
	global_load_lds_dwordx4 v[232:233], off
	s_cmp_eq_i32 s51, -2
	s_cselect_b32 s98, s2, 0
	s_cmp_lg_u32 s98, 0
	s_cbranch_scc1 .Lga_relax_l1w2
	s_waitcnt vmcnt(8)
	s_branch .Lga_join_l1w2

.Lga_join_l1w2:
	s_waitcnt lgkmcnt(0)
	s_barrier
	s_setprio 1
	s_waitcnt lgkmcnt(0)
	v_mfma_f32_16x16x32_bf16 v[66:69], v[134:137], v[186:189], v[66:69]
	v_mfma_f32_16x16x32_bf16 v[66:69], v[150:153], v[202:205], v[66:69]
	v_mfma_f32_16x16x32_bf16 v[62:65], v[154:157], v[186:189], v[62:65]
	v_mfma_f32_16x16x32_bf16 v[62:65], v[158:161], v[202:205], v[62:65]
	v_mfma_f32_16x16x32_bf16 v[50:53], v[134:137], v[206:209], v[50:53]
	v_mfma_f32_16x16x32_bf16 v[50:53], v[150:153], v[210:213], v[50:53]
	v_mfma_f32_16x16x32_bf16 v[46:49], v[154:157], v[206:209], v[46:49]
	v_mfma_f32_16x16x32_bf16 v[46:49], v[158:161], v[210:213], v[46:49]
	v_mfma_f32_16x16x32_bf16 v[34:37], v[134:137], v[214:217], v[34:37]
	v_mfma_f32_16x16x32_bf16 v[34:37], v[150:153], v[218:221], v[34:37]
	v_mfma_f32_16x16x32_bf16 v[30:33], v[154:157], v[214:217], v[30:33]
	v_mfma_f32_16x16x32_bf16 v[30:33], v[158:161], v[218:221], v[30:33]
	v_mfma_f32_16x16x32_bf16 v[18:21], v[134:137], v[222:225], v[18:21]
	v_mfma_f32_16x16x32_bf16 v[18:21], v[150:153], v[226:229], v[18:21]
	v_mfma_f32_16x16x32_bf16 v[10:13], v[154:157], v[222:225], v[10:13]
	v_mfma_f32_16x16x32_bf16 v[10:13], v[158:161], v[226:229], v[10:13]
	s_setprio 0
	s_setprio 1
	v_mfma_f32_16x16x32_bf16 v[58:61], v[162:165], v[186:189], v[58:61]
	v_mfma_f32_16x16x32_bf16 v[58:61], v[166:169], v[202:205], v[58:61]
	v_mfma_f32_16x16x32_bf16 v[54:57], v[170:173], v[186:189], v[54:57]
	v_mfma_f32_16x16x32_bf16 v[54:57], v[182:185], v[202:205], v[54:57]
	v_mfma_f32_16x16x32_bf16 v[42:45], v[162:165], v[206:209], v[42:45]
	v_mfma_f32_16x16x32_bf16 v[42:45], v[166:169], v[210:213], v[42:45]
	v_mfma_f32_16x16x32_bf16 v[38:41], v[170:173], v[206:209], v[38:41]
	v_mfma_f32_16x16x32_bf16 v[38:41], v[182:185], v[210:213], v[38:41]
	v_mfma_f32_16x16x32_bf16 v[26:29], v[162:165], v[214:217], v[26:29]
	v_mfma_f32_16x16x32_bf16 v[26:29], v[166:169], v[218:221], v[26:29]
	v_mfma_f32_16x16x32_bf16 v[22:25], v[170:173], v[214:217], v[22:25]
	v_mfma_f32_16x16x32_bf16 v[22:25], v[182:185], v[218:221], v[22:25]
	v_mfma_f32_16x16x32_bf16 v[6:9], v[162:165], v[222:225], v[6:9]
	v_mfma_f32_16x16x32_bf16 v[6:9], v[166:169], v[226:229], v[6:9]
	v_mfma_f32_16x16x32_bf16 v[2:5], v[170:173], v[222:225], v[2:5]
	v_mfma_f32_16x16x32_bf16 v[2:5], v[182:185], v[226:229], v[2:5]
	s_setprio 0
	s_barrier
	s_add_i32 s52, 0, 0x18000
	s_add_i32 s53, 0, 0x1c000
	v_add_u32_e32 v158, s52, v199
	v_add_u32_e32 v182, s53, v199
	ds_read_b128 v[134:137], v158
	ds_read_b128 v[150:153], v158 offset:1024
	ds_read_b128 v[154:157], v158 offset:2048
	ds_read_b128 v[158:161], v158 offset:3072
	ds_read_b128 v[162:165], v182
	ds_read_b128 v[166:169], v182 offset:1024
	ds_read_b128 v[170:173], v182 offset:2048
	ds_read_b128 v[182:185], v182 offset:3072
	s_add_u32 s34, s34, 0x40000
	s_addc_u32 s35, s35, 0
	s_mov_b32 m0, s41
	v_lshl_add_u64 v[234:235], s[34:35], 0, v[140:141]
	ds_read_b128 v[186:189], v201 offset:32768
	ds_read_b128 v[202:205], v201 offset:33792
	ds_read_b128 v[206:209], v201 offset:34816
	ds_read_b128 v[210:213], v201 offset:35840
	ds_read_b128 v[214:217], v201 offset:36864
	ds_read_b128 v[218:221], v201 offset:37888
	ds_read_b128 v[222:225], v201 offset:38912
	ds_read_b128 v[226:229], v201 offset:39936
	global_load_lds_dwordx4 v[234:235], off
	v_lshl_add_u64 v[234:235], s[34:35], 0, v[138:139]
	s_mov_b32 m0, s42
	s_nop 0
	global_load_lds_dwordx4 v[234:235], off
	s_waitcnt vmcnt(8)
	s_waitcnt lgkmcnt(0)
	s_barrier
	s_setprio 1
	s_waitcnt lgkmcnt(0)
	v_mfma_f32_16x16x32_bf16 v[130:133], v[134:137], v[186:189], v[130:133]
	v_mfma_f32_16x16x32_bf16 v[130:133], v[150:153], v[202:205], v[130:133]
	v_mfma_f32_16x16x32_bf16 v[126:129], v[154:157], v[186:189], v[126:129]
	v_mfma_f32_16x16x32_bf16 v[126:129], v[158:161], v[202:205], v[126:129]
	v_mfma_f32_16x16x32_bf16 v[114:117], v[134:137], v[206:209], v[114:117]
	v_mfma_f32_16x16x32_bf16 v[114:117], v[150:153], v[210:213], v[114:117]
	v_mfma_f32_16x16x32_bf16 v[110:113], v[154:157], v[206:209], v[110:113]
	v_mfma_f32_16x16x32_bf16 v[110:113], v[158:161], v[210:213], v[110:113]
	v_mfma_f32_16x16x32_bf16 v[98:101], v[134:137], v[214:217], v[98:101]
	v_mfma_f32_16x16x32_bf16 v[98:101], v[150:153], v[218:221], v[98:101]
	v_mfma_f32_16x16x32_bf16 v[94:97], v[154:157], v[214:217], v[94:97]
	v_mfma_f32_16x16x32_bf16 v[94:97], v[158:161], v[218:221], v[94:97]
	v_mfma_f32_16x16x32_bf16 v[82:85], v[134:137], v[222:225], v[82:85]
	v_mfma_f32_16x16x32_bf16 v[82:85], v[150:153], v[226:229], v[82:85]
	v_mfma_f32_16x16x32_bf16 v[78:81], v[154:157], v[222:225], v[78:81]
	v_mfma_f32_16x16x32_bf16 v[78:81], v[158:161], v[226:229], v[78:81]
	s_setprio 0
	s_setprio 1
	v_mfma_f32_16x16x32_bf16 v[122:125], v[162:165], v[186:189], v[122:125]
	v_mfma_f32_16x16x32_bf16 v[122:125], v[166:169], v[202:205], v[122:125]
	v_mfma_f32_16x16x32_bf16 v[118:121], v[170:173], v[186:189], v[118:121]
	v_mfma_f32_16x16x32_bf16 v[118:121], v[182:185], v[202:205], v[118:121]
	v_mfma_f32_16x16x32_bf16 v[106:109], v[162:165], v[206:209], v[106:109]
	v_mfma_f32_16x16x32_bf16 v[106:109], v[166:169], v[210:213], v[106:109]
	v_mfma_f32_16x16x32_bf16 v[102:105], v[170:173], v[206:209], v[102:105]
	v_mfma_f32_16x16x32_bf16 v[102:105], v[182:185], v[210:213], v[102:105]
	v_mfma_f32_16x16x32_bf16 v[90:93], v[162:165], v[214:217], v[90:93]
	v_mfma_f32_16x16x32_bf16 v[90:93], v[166:169], v[218:221], v[90:93]
	v_mfma_f32_16x16x32_bf16 v[86:89], v[170:173], v[214:217], v[86:89]
	v_mfma_f32_16x16x32_bf16 v[86:89], v[182:185], v[218:221], v[86:89]
	v_mfma_f32_16x16x32_bf16 v[74:77], v[162:165], v[222:225], v[74:77]
	v_mfma_f32_16x16x32_bf16 v[74:77], v[166:169], v[226:229], v[74:77]
	v_mfma_f32_16x16x32_bf16 v[70:73], v[170:173], v[222:225], v[70:73]
	v_mfma_f32_16x16x32_bf16 v[70:73], v[182:185], v[226:229], v[70:73]
	s_setprio 0
	s_barrier
	s_add_i32 s34, s52, s36
	v_lshl_add_u64 v[174:175], v[174:175], 0, s[92:93]
	s_mov_b32 m0, s34
	ds_read_b128 v[186:189], v201 offset:49152
	ds_read_b128 v[202:205], v201 offset:50176
	ds_read_b128 v[206:209], v201 offset:51200
	ds_read_b128 v[210:213], v201 offset:52224
	ds_read_b128 v[214:217], v201 offset:53248
	ds_read_b128 v[218:221], v201 offset:54272
	ds_read_b128 v[222:225], v201 offset:55296
	ds_read_b128 v[226:229], v201 offset:56320
	global_load_lds_dwordx4 v[174:175], off
	s_add_i32 m0, s34, 0x2000
	s_add_u32 s30, s30, 0x40080
	v_lshl_add_u64 v[174:175], v[190:191], 0, s[92:93]
	s_addc_u32 s31, s31, 0
	s_add_i32 s34, s53, s36
	global_load_lds_dwordx4 v[174:175], off
	v_lshl_add_u64 v[174:175], s[30:31], 0, v[0:1]
	s_mov_b32 m0, s34
	s_nop 0
	global_load_lds_dwordx4 v[174:175], off
	v_lshl_add_u64 v[174:175], s[30:31], 0, v[14:15]
	s_add_i32 m0, s34, 0x2000
	s_nop 0
	global_load_lds_dwordx4 v[174:175], off
	v_lshl_add_u64 v[174:175], v[230:231], 0, s[92:93]
	s_mov_b32 m0, s43
	s_nop 0
	global_load_lds_dwordx4 v[174:175], off
	v_lshl_add_u64 v[174:175], v[232:233], 0, s[92:93]
	s_mov_b32 m0, s44
	s_nop 0
	global_load_lds_dwordx4 v[174:175], off
	s_waitcnt vmcnt(8)
	s_waitcnt lgkmcnt(0)
	s_barrier
	s_setprio 1
	s_waitcnt lgkmcnt(0)
	v_mfma_f32_16x16x32_bf16 v[66:69], v[134:137], v[186:189], v[66:69]
	v_mfma_f32_16x16x32_bf16 v[66:69], v[150:153], v[202:205], v[66:69]
	v_mfma_f32_16x16x32_bf16 v[62:65], v[154:157], v[186:189], v[62:65]
	v_mfma_f32_16x16x32_bf16 v[62:65], v[158:161], v[202:205], v[62:65]
	v_mfma_f32_16x16x32_bf16 v[50:53], v[134:137], v[206:209], v[50:53]
	v_mfma_f32_16x16x32_bf16 v[50:53], v[150:153], v[210:213], v[50:53]
	v_mfma_f32_16x16x32_bf16 v[46:49], v[154:157], v[206:209], v[46:49]
	v_mfma_f32_16x16x32_bf16 v[46:49], v[158:161], v[210:213], v[46:49]
	v_mfma_f32_16x16x32_bf16 v[34:37], v[134:137], v[214:217], v[34:37]
	v_mfma_f32_16x16x32_bf16 v[34:37], v[150:153], v[218:221], v[34:37]
	v_mfma_f32_16x16x32_bf16 v[30:33], v[154:157], v[214:217], v[30:33]
	v_mfma_f32_16x16x32_bf16 v[30:33], v[158:161], v[218:221], v[30:33]
	v_mfma_f32_16x16x32_bf16 v[18:21], v[134:137], v[222:225], v[18:21]
	v_mfma_f32_16x16x32_bf16 v[18:21], v[150:153], v[226:229], v[18:21]
	v_mfma_f32_16x16x32_bf16 v[10:13], v[154:157], v[222:225], v[10:13]
	v_mfma_f32_16x16x32_bf16 v[10:13], v[158:161], v[226:229], v[10:13]
	s_setprio 0
	s_setprio 1
	v_mfma_f32_16x16x32_bf16 v[58:61], v[162:165], v[186:189], v[58:61]
	v_mfma_f32_16x16x32_bf16 v[58:61], v[166:169], v[202:205], v[58:61]
	v_mfma_f32_16x16x32_bf16 v[54:57], v[170:173], v[186:189], v[54:57]
	v_mfma_f32_16x16x32_bf16 v[54:57], v[182:185], v[202:205], v[54:57]
	v_mfma_f32_16x16x32_bf16 v[42:45], v[162:165], v[206:209], v[42:45]
	v_mfma_f32_16x16x32_bf16 v[42:45], v[166:169], v[210:213], v[42:45]
	v_mfma_f32_16x16x32_bf16 v[38:41], v[170:173], v[206:209], v[38:41]
	v_mfma_f32_16x16x32_bf16 v[38:41], v[182:185], v[210:213], v[38:41]
	v_mfma_f32_16x16x32_bf16 v[26:29], v[162:165], v[214:217], v[26:29]
	v_mfma_f32_16x16x32_bf16 v[26:29], v[166:169], v[218:221], v[26:29]
	v_mfma_f32_16x16x32_bf16 v[22:25], v[170:173], v[214:217], v[22:25]
	v_mfma_f32_16x16x32_bf16 v[22:25], v[182:185], v[218:221], v[22:25]
	v_mfma_f32_16x16x32_bf16 v[6:9], v[162:165], v[222:225], v[6:9]
	v_mfma_f32_16x16x32_bf16 v[6:9], v[166:169], v[226:229], v[6:9]
	v_mfma_f32_16x16x32_bf16 v[2:5], v[170:173], v[222:225], v[2:5]
	v_mfma_f32_16x16x32_bf16 v[2:5], v[182:185], v[226:229], v[2:5]
	s_setprio 0
	s_barrier
	s_add_i32 s51, s51, 2
	s_add_u32 s0, s0, 0x100
	s_addc_u32 s1, s1, 0
	s_add_u32 s49, s49, 0x100
	s_addc_u32 s50, s50, 0
	s_cmp_gt_u32 s51, 13
	s_cbranch_scc0 .LBB0_566
	s_and_b64 vcc, exec, s[18:19]
	s_cbranch_vccz .LBB0_569
	s_barrier

.LBB0_637:
	s_add_i32 s47, s24, 2
	s_add_u32 s48, s22, 0x80
	s_addc_u32 s25, s23, 0
	s_add_i32 s50, 0, 0x10000
	s_cmp_eq_u32 s40, s24
	s_cselect_b32 s25, s7, s25
	s_cselect_b32 s24, s6, s48
	v_add_u32_e32 v135, s50, v249
	s_cselect_b32 s49, s21, s46
	s_cselect_b32 s48, s20, s45
	s_add_i32 s51, 0, 0x14000
	ds_read_b128 v[142:145], v135
	ds_read_b128 v[146:149], v135 offset:1024
	ds_read_b128 v[150:153], v135 offset:2048
	ds_read_b128 v[154:157], v135 offset:3072
	v_add_u32_e32 v135, s51, v249
	ds_read_b128 v[158:161], v135
	ds_read_b128 v[162:165], v135 offset:1024
	ds_read_b128 v[166:169], v135 offset:2048
	ds_read_b128 v[170:173], v135 offset:3072
	v_lshl_add_u64 v[174:175], s[22:23], 0, v[138:139]
	s_add_i32 m0, s31, 0xc000
	ds_read_b128 v[182:185], v251
	ds_read_b128 v[186:189], v251 offset:1024
	ds_read_b128 v[190:193], v251 offset:2048
	ds_read_b128 v[194:197], v251 offset:3072
	ds_read_b128 v[198:201], v251 offset:4096
	ds_read_b128 v[202:205], v251 offset:5120
	ds_read_b128 v[206:209], v251 offset:6144
	ds_read_b128 v[210:213], v251 offset:7168
	global_load_lds_dwordx4 v[174:175], off
	v_lshl_add_u64 v[174:175], s[22:23], 0, v[140:141]
	s_add_i32 m0, s31, 0xe000
	s_nop 0
	global_load_lds_dwordx4 v[174:175], off
	s_cmp_eq_u32 s47, 2
	s_cselect_b32 s98, s41, 0
	s_cmp_gt_u32 s98, 1
	s_cbranch_scc1 .Lga_relax_l2w1
	s_waitcnt vmcnt(8)
	s_branch .Lga_join_l2w1
.Lga_relax_l2w1:
	s_waitcnt vmcnt(48)
.Lga_join_l2w1:
	s_waitcnt lgkmcnt(0)
	s_barrier
	s_setprio 1
	s_waitcnt lgkmcnt(0)
	v_mfma_f32_16x16x32_bf16 v[130:133], v[142:145], v[182:185], v[130:133]
	v_mfma_f32_16x16x32_bf16 v[130:133], v[146:149], v[186:189], v[130:133]
	v_mfma_f32_16x16x32_bf16 v[126:129], v[150:153], v[182:185], v[126:129]
	v_mfma_f32_16x16x32_bf16 v[126:129], v[154:157], v[186:189], v[126:129]
	v_mfma_f32_16x16x32_bf16 v[114:117], v[142:145], v[190:193], v[114:117]
	v_mfma_f32_16x16x32_bf16 v[114:117], v[146:149], v[194:197], v[114:117]
	v_mfma_f32_16x16x32_bf16 v[110:113], v[150:153], v[190:193], v[110:113]
	v_mfma_f32_16x16x32_bf16 v[110:113], v[154:157], v[194:197], v[110:113]
	v_mfma_f32_16x16x32_bf16 v[98:101], v[142:145], v[198:201], v[98:101]
	v_mfma_f32_16x16x32_bf16 v[98:101], v[146:149], v[202:205], v[98:101]
	v_mfma_f32_16x16x32_bf16 v[94:97], v[150:153], v[198:201], v[94:97]
	v_mfma_f32_16x16x32_bf16 v[94:97], v[154:157], v[202:205], v[94:97]
	v_mfma_f32_16x16x32_bf16 v[82:85], v[142:145], v[206:209], v[82:85]
	v_mfma_f32_16x16x32_bf16 v[82:85], v[146:149], v[210:213], v[82:85]
	v_mfma_f32_16x16x32_bf16 v[78:81], v[150:153], v[206:209], v[78:81]
	v_mfma_f32_16x16x32_bf16 v[78:81], v[154:157], v[210:213], v[78:81]
	s_setprio 0
	s_setprio 1
	v_mfma_f32_16x16x32_bf16 v[122:125], v[158:161], v[182:185], v[122:125]
	v_mfma_f32_16x16x32_bf16 v[122:125], v[162:165], v[186:189], v[122:125]
	v_mfma_f32_16x16x32_bf16 v[118:121], v[166:169], v[182:185], v[118:121]
	v_mfma_f32_16x16x32_bf16 v[118:121], v[170:173], v[186:189], v[118:121]
	v_mfma_f32_16x16x32_bf16 v[106:109], v[158:161], v[190:193], v[106:109]
	v_mfma_f32_16x16x32_bf16 v[106:109], v[162:165], v[194:197], v[106:109]
	v_mfma_f32_16x16x32_bf16 v[102:105], v[166:169], v[190:193], v[102:105]
	v_mfma_f32_16x16x32_bf16 v[102:105], v[170:173], v[194:197], v[102:105]
	v_mfma_f32_16x16x32_bf16 v[90:93], v[158:161], v[198:201], v[90:93]
	v_mfma_f32_16x16x32_bf16 v[90:93], v[162:165], v[202:205], v[90:93]
	v_mfma_f32_16x16x32_bf16 v[86:89], v[166:169], v[198:201], v[86:89]
	v_mfma_f32_16x16x32_bf16 v[86:89], v[170:173], v[202:205], v[86:89]
	v_mfma_f32_16x16x32_bf16 v[74:77], v[158:161], v[206:209], v[74:77]
	v_mfma_f32_16x16x32_bf16 v[74:77], v[162:165], v[210:213], v[74:77]
	v_mfma_f32_16x16x32_bf16 v[70:73], v[166:169], v[206:209], v[70:73]
	v_mfma_f32_16x16x32_bf16 v[70:73], v[170:173], v[210:213], v[70:73]
	s_setprio 0
	s_barrier
	s_add_i32 s50, s50, s30
	v_lshl_add_u64 v[174:175], s[48:49], 0, v[0:1]
	s_mov_b32 m0, s50
	ds_read_b128 v[182:185], v251 offset:16384
	ds_read_b128 v[186:189], v251 offset:17408
	ds_read_b128 v[190:193], v251 offset:18432
	ds_read_b128 v[194:197], v251 offset:19456
	ds_read_b128 v[198:201], v251 offset:20480
	ds_read_b128 v[202:205], v251 offset:21504
	ds_read_b128 v[206:209], v251 offset:22528
	ds_read_b128 v[210:213], v251 offset:23552
	global_load_lds_dwordx4 v[174:175], off
	s_add_i32 m0, s50, 0x2000
	v_lshl_add_u64 v[214:215], s[48:49], 0, v[14:15]
	s_add_u32 s48, s48, s10
	s_addc_u32 s49, s49, 0
	s_add_i32 s50, s51, s30
	global_load_lds_dwordx4 v[214:215], off
	v_lshl_add_u64 v[216:217], s[48:49], 0, v[0:1]
	s_mov_b32 m0, s50
	v_lshl_add_u64 v[218:219], s[48:49], 0, v[14:15]
	global_load_lds_dwordx4 v[216:217], off
	s_add_i32 m0, s50, 0x2000
	v_lshl_add_u64 v[220:221], s[24:25], 0, v[0:1]
	global_load_lds_dwordx4 v[218:219], off
	s_mov_b32 m0, s31
	v_lshl_add_u64 v[222:223], s[24:25], 0, v[14:15]
	global_load_lds_dwordx4 v[220:221], off
	s_mov_b32 m0, s34
	s_nop 0
	global_load_lds_dwordx4 v[222:223], off
	s_cmp_eq_u32 s47, 2
	s_cselect_b32 s98, s41, 0
	s_cmp_gt_u32 s98, 1
	s_cbranch_scc1 .Lga_relax_l2w2
	s_waitcnt vmcnt(8)
	s_branch .Lga_join_l2w2

.Lga_join_l2w2:
	s_waitcnt lgkmcnt(0)
	s_barrier
	s_setprio 1
	s_waitcnt lgkmcnt(0)
	v_mfma_f32_16x16x32_bf16 v[66:69], v[142:145], v[182:185], v[66:69]
	v_mfma_f32_16x16x32_bf16 v[66:69], v[146:149], v[186:189], v[66:69]
	v_mfma_f32_16x16x32_bf16 v[62:65], v[150:153], v[182:185], v[62:65]
	v_mfma_f32_16x16x32_bf16 v[62:65], v[154:157], v[186:189], v[62:65]
	v_mfma_f32_16x16x32_bf16 v[50:53], v[142:145], v[190:193], v[50:53]
	v_mfma_f32_16x16x32_bf16 v[50:53], v[146:149], v[194:197], v[50:53]
	v_mfma_f32_16x16x32_bf16 v[46:49], v[150:153], v[190:193], v[46:49]
	v_mfma_f32_16x16x32_bf16 v[46:49], v[154:157], v[194:197], v[46:49]
	v_mfma_f32_16x16x32_bf16 v[34:37], v[142:145], v[198:201], v[34:37]
	v_mfma_f32_16x16x32_bf16 v[34:37], v[146:149], v[202:205], v[34:37]
	v_mfma_f32_16x16x32_bf16 v[30:33], v[150:153], v[198:201], v[30:33]
	v_mfma_f32_16x16x32_bf16 v[30:33], v[154:157], v[202:205], v[30:33]
	v_mfma_f32_16x16x32_bf16 v[18:21], v[142:145], v[206:209], v[18:21]
	v_mfma_f32_16x16x32_bf16 v[18:21], v[146:149], v[210:213], v[18:21]
	v_mfma_f32_16x16x32_bf16 v[10:13], v[150:153], v[206:209], v[10:13]
	v_mfma_f32_16x16x32_bf16 v[10:13], v[154:157], v[210:213], v[10:13]
	s_setprio 0
	s_setprio 1
	v_mfma_f32_16x16x32_bf16 v[58:61], v[158:161], v[182:185], v[58:61]
	v_mfma_f32_16x16x32_bf16 v[58:61], v[162:165], v[186:189], v[58:61]
	v_mfma_f32_16x16x32_bf16 v[54:57], v[166:169], v[182:185], v[54:57]
	v_mfma_f32_16x16x32_bf16 v[54:57], v[170:173], v[186:189], v[54:57]
	v_mfma_f32_16x16x32_bf16 v[42:45], v[158:161], v[190:193], v[42:45]
	v_mfma_f32_16x16x32_bf16 v[42:45], v[162:165], v[194:197], v[42:45]
	v_mfma_f32_16x16x32_bf16 v[38:41], v[166:169], v[190:193], v[38:41]
	v_mfma_f32_16x16x32_bf16 v[38:41], v[170:173], v[194:197], v[38:41]
	v_mfma_f32_16x16x32_bf16 v[26:29], v[158:161], v[198:201], v[26:29]
	v_mfma_f32_16x16x32_bf16 v[26:29], v[162:165], v[202:205], v[26:29]
	v_mfma_f32_16x16x32_bf16 v[22:25], v[166:169], v[198:201], v[22:25]
	v_mfma_f32_16x16x32_bf16 v[22:25], v[170:173], v[202:205], v[22:25]
	v_mfma_f32_16x16x32_bf16 v[6:9], v[158:161], v[206:209], v[6:9]
	v_mfma_f32_16x16x32_bf16 v[6:9], v[162:165], v[210:213], v[6:9]
	v_mfma_f32_16x16x32_bf16 v[2:5], v[166:169], v[206:209], v[2:5]
	v_mfma_f32_16x16x32_bf16 v[2:5], v[170:173], v[210:213], v[2:5]
	s_setprio 0
	s_barrier
	s_add_i32 s48, 0, 0x18000
	v_add_u32_e32 v135, s48, v249
	s_add_i32 s49, 0, 0x1c000
	ds_read_b128 v[142:145], v135
	ds_read_b128 v[146:149], v135 offset:1024
	ds_read_b128 v[150:153], v135 offset:2048
	ds_read_b128 v[154:157], v135 offset:3072
	v_add_u32_e32 v135, s49, v249
	ds_read_b128 v[158:161], v135
	ds_read_b128 v[162:165], v135 offset:1024
	ds_read_b128 v[166:169], v135 offset:2048
	ds_read_b128 v[170:173], v135 offset:3072
	s_add_u32 s24, s24, s10
	s_addc_u32 s25, s25, 0
	s_mov_b32 m0, s35
	v_lshl_add_u64 v[224:225], s[24:25], 0, v[0:1]
	ds_read_b128 v[182:185], v251 offset:32768
	ds_read_b128 v[186:189], v251 offset:33792
	ds_read_b128 v[190:193], v251 offset:34816
	ds_read_b128 v[194:197], v251 offset:35840
	ds_read_b128 v[198:201], v251 offset:36864
	ds_read_b128 v[202:205], v251 offset:37888
	ds_read_b128 v[206:209], v251 offset:38912
	ds_read_b128 v[210:213], v251 offset:39936
	global_load_lds_dwordx4 v[224:225], off
	v_lshl_add_u64 v[224:225], s[24:25], 0, v[14:15]
	s_mov_b32 m0, s36
	s_nop 0
	global_load_lds_dwordx4 v[224:225], off
	s_waitcnt vmcnt(8)
	s_waitcnt lgkmcnt(0)
	s_barrier
	s_setprio 1
	s_waitcnt lgkmcnt(0)
	v_mfma_f32_16x16x32_bf16 v[130:133], v[142:145], v[182:185], v[130:133]
	v_mfma_f32_16x16x32_bf16 v[130:133], v[146:149], v[186:189], v[130:133]
	v_mfma_f32_16x16x32_bf16 v[126:129], v[150:153], v[182:185], v[126:129]
	v_mfma_f32_16x16x32_bf16 v[126:129], v[154:157], v[186:189], v[126:129]
	v_mfma_f32_16x16x32_bf16 v[114:117], v[142:145], v[190:193], v[114:117]
	v_mfma_f32_16x16x32_bf16 v[114:117], v[146:149], v[194:197], v[114:117]
	v_mfma_f32_16x16x32_bf16 v[110:113], v[150:153], v[190:193], v[110:113]
	v_mfma_f32_16x16x32_bf16 v[110:113], v[154:157], v[194:197], v[110:113]
	v_mfma_f32_16x16x32_bf16 v[98:101], v[142:145], v[198:201], v[98:101]
	v_mfma_f32_16x16x32_bf16 v[98:101], v[146:149], v[202:205], v[98:101]
	v_mfma_f32_16x16x32_bf16 v[94:97], v[150:153], v[198:201], v[94:97]
	v_mfma_f32_16x16x32_bf16 v[94:97], v[154:157], v[202:205], v[94:97]
	v_mfma_f32_16x16x32_bf16 v[82:85], v[142:145], v[206:209], v[82:85]
	v_mfma_f32_16x16x32_bf16 v[82:85], v[146:149], v[210:213], v[82:85]
	v_mfma_f32_16x16x32_bf16 v[78:81], v[150:153], v[206:209], v[78:81]
	v_mfma_f32_16x16x32_bf16 v[78:81], v[154:157], v[210:213], v[78:81]
	s_setprio 0
	s_setprio 1
	v_mfma_f32_16x16x32_bf16 v[122:125], v[158:161], v[182:185], v[122:125]
	v_mfma_f32_16x16x32_bf16 v[122:125], v[162:165], v[186:189], v[122:125]
	v_mfma_f32_16x16x32_bf16 v[118:121], v[166:169], v[182:185], v[118:121]
	v_mfma_f32_16x16x32_bf16 v[118:121], v[170:173], v[186:189], v[118:121]
	v_mfma_f32_16x16x32_bf16 v[106:109], v[158:161], v[190:193], v[106:109]
	v_mfma_f32_16x16x32_bf16 v[106:109], v[162:165], v[194:197], v[106:109]
	v_mfma_f32_16x16x32_bf16 v[102:105], v[166:169], v[190:193], v[102:105]
	v_mfma_f32_16x16x32_bf16 v[102:105], v[170:173], v[194:197], v[102:105]
	v_mfma_f32_16x16x32_bf16 v[90:93], v[158:161], v[198:201], v[90:93]
	v_mfma_f32_16x16x32_bf16 v[90:93], v[162:165], v[202:205], v[90:93]
	v_mfma_f32_16x16x32_bf16 v[86:89], v[166:169], v[198:201], v[86:89]
	v_mfma_f32_16x16x32_bf16 v[86:89], v[170:173], v[202:205], v[86:89]
	v_mfma_f32_16x16x32_bf16 v[74:77], v[158:161], v[206:209], v[74:77]
	v_mfma_f32_16x16x32_bf16 v[74:77], v[162:165], v[210:213], v[74:77]
	v_mfma_f32_16x16x32_bf16 v[70:73], v[166:169], v[206:209], v[70:73]
	v_mfma_f32_16x16x32_bf16 v[70:73], v[170:173], v[210:213], v[70:73]
	s_setprio 0
	s_barrier
	s_add_i32 s24, s48, s30
	v_lshl_add_u64 v[174:175], v[174:175], 0, s[92:93]
	s_mov_b32 m0, s24
	ds_read_b128 v[182:185], v251 offset:49152
	ds_read_b128 v[186:189], v251 offset:50176
	ds_read_b128 v[190:193], v251 offset:51200
	ds_read_b128 v[194:197], v251 offset:52224
	ds_read_b128 v[198:201], v251 offset:53248
	ds_read_b128 v[202:205], v251 offset:54272
	ds_read_b128 v[206:209], v251 offset:55296
	ds_read_b128 v[210:213], v251 offset:56320
	global_load_lds_dwordx4 v[174:175], off
	v_lshl_add_u64 v[174:175], v[214:215], 0, s[92:93]
	s_add_i32 m0, s24, 0x2000
	s_add_i32 s24, s49, s30
	global_load_lds_dwordx4 v[174:175], off
	v_lshl_add_u64 v[174:175], v[216:217], 0, s[92:93]
	s_mov_b32 m0, s24
	s_nop 0
	global_load_lds_dwordx4 v[174:175], off
	v_lshl_add_u64 v[174:175], v[218:219], 0, s[92:93]
	s_add_i32 m0, s24, 0x2000
	s_nop 0
	global_load_lds_dwordx4 v[174:175], off
	v_lshl_add_u64 v[174:175], v[220:221], 0, s[92:93]
	s_mov_b32 m0, s37
	s_nop 0
	global_load_lds_dwordx4 v[174:175], off
	v_lshl_add_u64 v[174:175], v[222:223], 0, s[92:93]
	s_mov_b32 m0, s38
	s_nop 0
	global_load_lds_dwordx4 v[174:175], off
	s_waitcnt vmcnt(8)
	s_waitcnt lgkmcnt(0)
	s_barrier
	s_setprio 1
	s_waitcnt lgkmcnt(0)
	v_mfma_f32_16x16x32_bf16 v[66:69], v[142:145], v[182:185], v[66:69]
	v_mfma_f32_16x16x32_bf16 v[66:69], v[146:149], v[186:189], v[66:69]
	v_mfma_f32_16x16x32_bf16 v[62:65], v[150:153], v[182:185], v[62:65]
	v_mfma_f32_16x16x32_bf16 v[62:65], v[154:157], v[186:189], v[62:65]
	v_mfma_f32_16x16x32_bf16 v[50:53], v[142:145], v[190:193], v[50:53]
	v_mfma_f32_16x16x32_bf16 v[50:53], v[146:149], v[194:197], v[50:53]
	v_mfma_f32_16x16x32_bf16 v[46:49], v[150:153], v[190:193], v[46:49]
	v_mfma_f32_16x16x32_bf16 v[46:49], v[154:157], v[194:197], v[46:49]
	v_mfma_f32_16x16x32_bf16 v[34:37], v[142:145], v[198:201], v[34:37]
	v_mfma_f32_16x16x32_bf16 v[34:37], v[146:149], v[202:205], v[34:37]
	v_mfma_f32_16x16x32_bf16 v[30:33], v[150:153], v[198:201], v[30:33]
	v_mfma_f32_16x16x32_bf16 v[30:33], v[154:157], v[202:205], v[30:33]
	v_mfma_f32_16x16x32_bf16 v[18:21], v[142:145], v[206:209], v[18:21]
	v_mfma_f32_16x16x32_bf16 v[18:21], v[146:149], v[210:213], v[18:21]
	v_mfma_f32_16x16x32_bf16 v[10:13], v[150:153], v[206:209], v[10:13]
	v_mfma_f32_16x16x32_bf16 v[10:13], v[154:157], v[210:213], v[10:13]
	s_setprio 0
	s_setprio 1
	v_mfma_f32_16x16x32_bf16 v[58:61], v[158:161], v[182:185], v[58:61]
	v_mfma_f32_16x16x32_bf16 v[58:61], v[162:165], v[186:189], v[58:61]
	v_mfma_f32_16x16x32_bf16 v[54:57], v[166:169], v[182:185], v[54:57]
	v_mfma_f32_16x16x32_bf16 v[54:57], v[170:173], v[186:189], v[54:57]
	v_mfma_f32_16x16x32_bf16 v[42:45], v[158:161], v[190:193], v[42:45]
	v_mfma_f32_16x16x32_bf16 v[42:45], v[162:165], v[194:197], v[42:45]
	v_mfma_f32_16x16x32_bf16 v[38:41], v[166:169], v[190:193], v[38:41]
	v_mfma_f32_16x16x32_bf16 v[38:41], v[170:173], v[194:197], v[38:41]
	v_mfma_f32_16x16x32_bf16 v[26:29], v[158:161], v[198:201], v[26:29]
	v_mfma_f32_16x16x32_bf16 v[26:29], v[162:165], v[202:205], v[26:29]
	v_mfma_f32_16x16x32_bf16 v[22:25], v[166:169], v[198:201], v[22:25]
	v_mfma_f32_16x16x32_bf16 v[22:25], v[170:173], v[202:205], v[22:25]
	v_mfma_f32_16x16x32_bf16 v[6:9], v[158:161], v[206:209], v[6:9]
	v_mfma_f32_16x16x32_bf16 v[6:9], v[162:165], v[210:213], v[6:9]
	v_mfma_f32_16x16x32_bf16 v[2:5], v[166:169], v[206:209], v[2:5]
	v_mfma_f32_16x16x32_bf16 v[2:5], v[170:173], v[210:213], v[2:5]
	s_setprio 0
	s_barrier
	s_add_u32 s22, s22, 0x100
	s_addc_u32 s23, s23, 0
	s_add_u32 s45, s45, 0x100
	s_addc_u32 s46, s46, 0
	s_cmp_ge_u32 s47, s39
	s_mov_b32 s24, s47
	s_cbranch_scc0 .LBB0_637
	s_and_b64 vcc, exec, s[18:19]
	s_cbranch_vccz .LBB0_640
	s_barrier
